# v21 + P4 first-unit RMS factors formed in the phase prologue + P3 mid-K hook factors loaded one K-iteration earlier (no vmcnt(0) drain)
# baseline (speedup 1.0000x reference)
;     __device__ __forceinline__ void mid(f32x4 (&acc)[2][2][4][2], const Unit& u, int wr, int wc, int fr, int fq) const {
;         const int row0 = u.pm * BM + wr * 64 + fr;
; #pragma unroll
;         for (int ai = 0; ai < 2; ++ai)
; #pragma unroll
;             for (int m = 0; m < 4; ++m) { const float r = ra[row0 + ai * HALF + m * 16];
; #pragma unroll
;                 for (int bj = 0; bj < 2; ++bj)
; #pragma unroll
;                     for (int n = 0; n < 2; ++n) acc[ai][bj][m][n] = acc[ai][bj][m][n] * r; }
;     }
; template <class Epi, class Sched, bool ALIGN_EPI = false, bool SP2 = false, bool ABLK = false>
; __device__ __forceinline__ void gemm_phase(PG8_LAS unsigned char* lds, const Gemm g, const Sched& S, const Epi& E) {
;     ...
;             if constexpr (Epi::MID) { if (t == nt / 2) E.mid(acc, cur, wr, wc, fr, fq); }
.LBB0_482:
	s_cmpk_lg_i32 s40, 0x300
	s_cbranch_scc1 .Lp3_nora
	global_load_dword v246, v[132:133], off
	global_load_dword v247, v[132:133], off offset:64
	global_load_dword v248, v[132:133], off offset:128
	global_load_dword v249, v[132:133], off offset:192
	global_load_dword v250, v[132:133], off offset:512
	global_load_dword v251, v[132:133], off offset:576
	global_load_dword v252, v[132:133], off offset:640
	global_load_dword v253, v[132:133], off offset:704
.Lp3_nora:
	s_cmpk_lg_i32 s40, 0x400
	s_cbranch_scc1 .LBB0_481
	v_pk_mul_f32 v[130:131], v[130:131], v[246:247] op_sel_hi:[1,0]
	v_pk_mul_f32 v[128:129], v[128:129], v[246:247] op_sel_hi:[1,0]
	v_pk_mul_f32 v[126:127], v[126:127], v[246:247] op_sel_hi:[1,0]
	v_pk_mul_f32 v[124:125], v[124:125], v[246:247] op_sel_hi:[1,0]
	v_pk_mul_f32 v[122:123], v[122:123], v[246:247] op_sel_hi:[1,0]
	v_pk_mul_f32 v[120:121], v[120:121], v[246:247] op_sel_hi:[1,0]
	v_pk_mul_f32 v[118:119], v[118:119], v[246:247] op_sel_hi:[1,0]
	v_pk_mul_f32 v[116:117], v[116:117], v[246:247] op_sel_hi:[1,0]
	v_pk_mul_f32 v[114:115], v[114:115], v[246:247] op_sel:[0,1] op_sel_hi:[1,1]
	v_pk_mul_f32 v[112:113], v[112:113], v[246:247] op_sel:[0,1] op_sel_hi:[1,1]
	v_pk_mul_f32 v[110:111], v[110:111], v[246:247] op_sel:[0,1] op_sel_hi:[1,1]
	v_pk_mul_f32 v[108:109], v[108:109], v[246:247] op_sel:[0,1] op_sel_hi:[1,1]
	v_pk_mul_f32 v[106:107], v[106:107], v[246:247] op_sel:[0,1] op_sel_hi:[1,1]
	v_pk_mul_f32 v[104:105], v[104:105], v[246:247] op_sel:[0,1] op_sel_hi:[1,1]
	v_pk_mul_f32 v[102:103], v[102:103], v[246:247] op_sel:[0,1] op_sel_hi:[1,1]
	v_pk_mul_f32 v[100:101], v[100:101], v[246:247] op_sel:[0,1] op_sel_hi:[1,1]
	v_pk_mul_f32 v[98:99], v[98:99], v[248:249] op_sel_hi:[1,0]
	v_pk_mul_f32 v[96:97], v[96:97], v[248:249] op_sel_hi:[1,0]
	v_pk_mul_f32 v[94:95], v[94:95], v[248:249] op_sel_hi:[1,0]
	v_pk_mul_f32 v[92:93], v[92:93], v[248:249] op_sel_hi:[1,0]
	v_pk_mul_f32 v[90:91], v[90:91], v[248:249] op_sel_hi:[1,0]
	v_pk_mul_f32 v[88:89], v[88:89], v[248:249] op_sel_hi:[1,0]
	v_pk_mul_f32 v[86:87], v[86:87], v[248:249] op_sel_hi:[1,0]
	v_pk_mul_f32 v[84:85], v[84:85], v[248:249] op_sel_hi:[1,0]
	v_pk_mul_f32 v[82:83], v[82:83], v[248:249] op_sel:[0,1] op_sel_hi:[1,1]
	v_pk_mul_f32 v[80:81], v[80:81], v[248:249] op_sel:[0,1] op_sel_hi:[1,1]
	v_pk_mul_f32 v[78:79], v[78:79], v[248:249] op_sel:[0,1] op_sel_hi:[1,1]
	v_pk_mul_f32 v[76:77], v[76:77], v[248:249] op_sel:[0,1] op_sel_hi:[1,1]
	v_pk_mul_f32 v[74:75], v[74:75], v[248:249] op_sel:[0,1] op_sel_hi:[1,1]
	v_pk_mul_f32 v[72:73], v[72:73], v[248:249] op_sel:[0,1] op_sel_hi:[1,1]
	v_pk_mul_f32 v[70:71], v[70:71], v[248:249] op_sel:[0,1] op_sel_hi:[1,1]
	v_pk_mul_f32 v[68:69], v[68:69], v[248:249] op_sel:[0,1] op_sel_hi:[1,1]
	v_pk_mul_f32 v[66:67], v[66:67], v[250:251] op_sel_hi:[1,0]
	v_pk_mul_f32 v[64:65], v[64:65], v[250:251] op_sel_hi:[1,0]
	v_pk_mul_f32 v[62:63], v[62:63], v[250:251] op_sel_hi:[1,0]
	v_pk_mul_f32 v[60:61], v[60:61], v[250:251] op_sel_hi:[1,0]
	v_pk_mul_f32 v[58:59], v[58:59], v[250:251] op_sel_hi:[1,0]
	v_pk_mul_f32 v[56:57], v[56:57], v[250:251] op_sel_hi:[1,0]
	v_pk_mul_f32 v[54:55], v[54:55], v[250:251] op_sel_hi:[1,0]
	v_pk_mul_f32 v[52:53], v[52:53], v[250:251] op_sel_hi:[1,0]
	v_pk_mul_f32 v[50:51], v[50:51], v[250:251] op_sel:[0,1] op_sel_hi:[1,1]
	v_pk_mul_f32 v[48:49], v[48:49], v[250:251] op_sel:[0,1] op_sel_hi:[1,1]
	v_pk_mul_f32 v[46:47], v[46:47], v[250:251] op_sel:[0,1] op_sel_hi:[1,1]
	v_pk_mul_f32 v[44:45], v[44:45], v[250:251] op_sel:[0,1] op_sel_hi:[1,1]
	v_pk_mul_f32 v[42:43], v[42:43], v[250:251] op_sel:[0,1] op_sel_hi:[1,1]
	v_pk_mul_f32 v[40:41], v[40:41], v[250:251] op_sel:[0,1] op_sel_hi:[1,1]
	v_pk_mul_f32 v[38:39], v[38:39], v[250:251] op_sel:[0,1] op_sel_hi:[1,1]
	v_pk_mul_f32 v[36:37], v[36:37], v[250:251] op_sel:[0,1] op_sel_hi:[1,1]
	v_pk_mul_f32 v[34:35], v[34:35], v[252:253] op_sel_hi:[1,0]
	v_pk_mul_f32 v[32:33], v[32:33], v[252:253] op_sel_hi:[1,0]
	v_pk_mul_f32 v[30:31], v[30:31], v[252:253] op_sel_hi:[1,0]
	v_pk_mul_f32 v[28:29], v[28:29], v[252:253] op_sel_hi:[1,0]
	v_pk_mul_f32 v[26:27], v[26:27], v[252:253] op_sel_hi:[1,0]
	v_pk_mul_f32 v[24:25], v[24:25], v[252:253] op_sel_hi:[1,0]
	v_pk_mul_f32 v[22:23], v[22:23], v[252:253] op_sel_hi:[1,0]
	v_pk_mul_f32 v[20:21], v[20:21], v[252:253] op_sel_hi:[1,0]
	v_pk_mul_f32 v[18:19], v[18:19], v[252:253] op_sel:[0,1] op_sel_hi:[1,1]
	v_pk_mul_f32 v[16:17], v[16:17], v[252:253] op_sel:[0,1] op_sel_hi:[1,1]
	v_pk_mul_f32 v[14:15], v[14:15], v[252:253] op_sel:[0,1] op_sel_hi:[1,1]
	v_pk_mul_f32 v[12:13], v[12:13], v[252:253] op_sel:[0,1] op_sel_hi:[1,1]
	v_pk_mul_f32 v[10:11], v[10:11], v[252:253] op_sel:[0,1] op_sel_hi:[1,1]
	v_pk_mul_f32 v[8:9], v[8:9], v[252:253] op_sel:[0,1] op_sel_hi:[1,1]
	v_pk_mul_f32 v[6:7], v[6:7], v[252:253] op_sel:[0,1] op_sel_hi:[1,1]
	v_pk_mul_f32 v[4:5], v[4:5], v[252:253] op_sel:[0,1] op_sel_hi:[1,1]
	s_branch .LBB0_481

; #define PG8_STAGE(bufoff, gbase, voff) do { _Pragma("unroll") for (int _i = 0; _i < 2; ++_i) \
;         __builtin_amdgcn_global_load_lds((const unsigned*)((const char*)(gbase) + (voff)[_i]), (PG8_LAS unsigned*)(lds + (bufoff) + ldsw + _i * 8192), 16, 0, 0); } while (0)
; #define PG8_WAIT_V(n) asm volatile("s_waitcnt vmcnt(" #n ")" ::: "memory")
; #define PG8_BAR __builtin_amdgcn_s_barrier()
; template <class Epi, class Sched, bool ALIGN_EPI = false, bool SP2 = false, bool ABLK = false>
; __device__ __forceinline__ void gemm_phase(PG8_LAS unsigned char* lds, const Gemm g, const Sched& S, const Epi& E) {
;     ...
;     const int tid = tid_, wid = __builtin_amdgcn_readfirstlane(tid >> 6), lane = tid & 63, wr = wid >> 2, wc = wid & 3, fr = lane & 15, fq = lane >> 4;
;     const int K = g.K, nt = K / BK;
;     unsigned voffA[2], voffB[2];
; #pragma unroll
;     for (int i = 0; i < 2; ++i) { int R, C; stage_rc(tid * 16 + i * 8192, R, C); const int Rb = Epi::PERM ? ((R & ~31) + perm32(R & 31)) : R;
;         voffA[i] = (unsigned)(R * (ABLK ? BK : K) + C) * 2u; voffB[i] = (unsigned)(Rb * K + C) * 2u; }
;     const size_t kstep = (size_t)(BK * 2);
;     const size_t hstep = (size_t)HALF * K * 2;
;     const size_t tstep = 2 * hstep;
;     const size_t kstepA = ABLK ? (size_t)(BM * BK * 2) : kstep, hstepA = ABLK ? (size_t)(HALF * BK * 2) : hstep, tstepA = ABLK ? (size_t)nt * (BM * BK * 2) : tstep;
;     const unsigned ldsw = (unsigned)wid * 1024u;
;     const int aoff = lds_byte(wr * 64 + fr, fq * 8), boff = lds_byte(wc * 32 + fr, fq * 8);
;     ...
;         PG8_STAGE(PG8_SB(0, 0), cB, voffB); PG8_STAGE(PG8_SB(0, 1), cB + hstep, voffB); PG8_STAGE(PG8_SA(0, 0), cA, voffA); PG8_STAGE(PG8_SA(0, 1), cA + hstepA, voffA);
;         if (wr == 1) PG8_BAR;
;         PG8_WAIT_V(2); PG8_BAR;
;         PG8_STAGE(PG8_SB(1, 0), cB + kstep, voffB); PG8_STAGE(PG8_SA(1, 0), cA + kstepA, voffA); PG8_STAGE(PG8_SB(1, 1), cB + hstep + kstep, voffB);
;         PG8_WAIT_V(6); PG8_BAR;
.LBB0_528:
	s_lshl_b32 s7, s16, 5
	s_mov_b64 s[16:17], 0x80
	s_and_b32 s54, s7, 0x60
	s_add_i32 m0, s40, 0x18000
	v_lshl_add_u64 v[2:3], v[2:3], 0, s[16:17]
	s_lshl_b32 s2, s19, 13
	s_lshl_b32 s24, s54, 7
	s_waitcnt vmcnt(2)
	s_barrier
	global_load_lds_dwordx4 v[2:3], off
	s_add_i32 m0, s40, 0x1a000
	s_add_u32 s22, s36, 0x8000
	v_lshl_add_u64 v[0:1], v[0:1], 0, s[16:17]
	s_addc_u32 s23, s37, 0
	s_add_i32 s55, s40, 0x8000
	global_load_lds_dwordx4 v[0:1], off
	v_lshl_add_u64 v[0:1], s[22:23], 0, v[138:139]
	s_mov_b32 m0, s55
	s_add_i32 s56, s40, 0xa000
	global_load_lds_dwordx4 v[0:1], off
	v_lshl_add_u64 v[0:1], s[22:23], 0, v[134:135]
	s_add_u32 s22, s34, 0x40080
	s_mov_b32 m0, s56
	s_addc_u32 s23, s35, 0
	global_load_lds_dwordx4 v[0:1], off
	s_add_i32 m0, s40, 0x1c000
	v_lshl_add_u64 v[0:1], s[22:23], 0, v[136:137]
	global_load_lds_dwordx4 v[0:1], off
	v_lshl_add_u64 v[0:1], s[22:23], 0, v[132:133]
	s_add_i32 m0, s40, 0x1e000
	s_cmpk_lt_u32 s18, 0x100
	global_load_lds_dwordx4 v[0:1], off
	v_bfe_u32 v1, v7, 4, 2
	v_and_b32_e32 v0, 15, v7
	v_lshlrev_b32_e32 v2, 3, v1
	v_lshlrev_b32_e32 v140, 4, v1
	v_lshlrev_b32_e32 v1, 2, v7
	v_lshl_or_b32 v142, s19, 6, v0
	v_lshl_or_b32 v0, v0, 6, v140
	v_and_b32_e32 v1, 32, v1
	v_bitop3_b32 v7, v0, s2, v1 bitop3:0xde
	v_bitop3_b32 v166, v0, s24, v1 bitop3:0xde
	v_and_or_b32 v0, s7, 32, v2
	v_or_b32_e32 v2, 16, v142
	v_ashrrev_i32_e32 v3, 31, v2
	v_lshlrev_b64 v[146:147], 7, v[2:3]
	v_or_b32_e32 v2, 32, v142
	v_ashrrev_i32_e32 v3, 31, v2
	v_lshlrev_b64 v[148:149], 7, v[2:3]
	v_or_b32_e32 v2, 48, v142
	v_lshlrev_b32_e32 v1, 10, v9
	v_ashrrev_i32_e32 v3, 31, v2
	v_and_b32_e32 v1, 0xfffff800, v1
	v_lshlrev_b64 v[150:151], 7, v[2:3]
	v_lshl_add_u32 v1, v8, 7, v1
	v_and_b32_e32 v2, 1, v9
	v_ashrrev_i32_e32 v143, 31, v142
	v_lshl_or_b32 v1, v2, 6, v1
	v_lshlrev_b64 v[144:145], 7, v[142:143]
	v_lshl_add_u32 v162, v10, 1, v1
	v_lshlrev_b32_e32 v1, 10, v4
	v_lshl_add_u64 v[152:153], v[144:145], 0, s[20:21]
	s_mov_b64 s[20:21], 0x4800
	v_and_b32_e32 v1, 0xfffff800, v1
	s_waitcnt vmcnt(6)
	v_lshl_add_u64 v[154:155], v[144:145], 0, s[20:21]
	s_mov_b64 s[20:21], 0x5000
	v_lshl_add_u32 v1, v5, 7, v1
	v_and_b32_e32 v2, 1, v4
	s_cselect_b64 s[18:19], -1, 0
	v_lshl_add_u64 v[156:157], v[144:145], 0, s[20:21]
	s_mov_b64 s[20:21], 0x5800
	v_lshl_or_b32 v1, v2, 6, v1
	s_add_i32 s60, 0, 0x10000
	s_add_i32 s57, 0, 0x14000
	v_lshl_add_u64 v[158:159], v[144:145], 0, s[20:21]
	v_lshl_add_u64 v[160:161], s[8:9], 0, v[140:141]
	v_mov_b32_e32 v163, v141
	v_lshl_add_u32 v164, v6, 1, v1
	v_mov_b32_e32 v165, v141
	v_add_u32_e32 v143, s60, v166
	v_add_u32_e32 v167, s57, v166
	v_add_u32_e32 v168, 0, v7
	v_mbcnt_hi_u32_b32 v169, -1, v179
	v_mov_b32_e32 v170, 0x358637bd
	v_lshlrev_b32_e32 v140, 1, v0
	s_add_i32 s58, s40, 0xc000
	s_add_i32 s59, s40, 0xe000
	s_add_i32 s60, s60, s3
	s_cmp_eq_u32 s30, s100
	s_cbranch_scc1 .Lp4_r2_cached0
;     __device__ __forceinline__ void operator()(const f32x4 (&acc)[2][2][4][2], const Unit& u, int wr, int wc, int fr, int fq) const {
;     ...
;             for (int m = 0; m < 4; ++m) pv[ai][m] = __builtin_nontemporal_load((const f32x4*)(part + (size_t)(row0 + ai * HALF + m * 16) * 16 + 4 * fq));
;         float r2[2][4];
; #pragma unroll
;         for (int ai = 0; ai < 2; ++ai)
; #pragma unroll
;             for (int m = 0; m < 4; ++m) { float s = (pv[ai][m][0] + pv[ai][m][1]) + (pv[ai][m][2] + pv[ai][m][3]); s += __shfl_xor(s, 16); s += __shfl_xor(s, 32); r2[ai][m] = 1.0f / (s * (1.0f / 1024.0f) + eps); }
	s_mov_b32 s100, s30
	v_lshl_add_u32 v204, s30, 8, v142
	v_mov_b32_e32 v205, 0
	v_lshlrev_b64 v[206:207], 6, v[204:205]
	v_xor_b32_e32 v240, 16, v169
	v_lshl_add_u64 v[206:207], v[160:161], 0, v[206:207]
	v_xor_b32_e32 v241, 32, v169
	global_load_dwordx4 v[208:211], v[206:207], off nt
	global_load_dwordx4 v[212:215], v[206:207], off offset:1024 nt
	global_load_dwordx4 v[216:219], v[206:207], off offset:2048 nt
	global_load_dwordx4 v[220:223], v[206:207], off offset:3072 nt
	v_add_co_u32_e32 v242, vcc, 0x2000, v206
	v_lshlrev_b32_e32 v240, 2, v240
	s_nop 0
	v_addc_co_u32_e32 v243, vcc, 0, v207, vcc
	v_lshlrev_b32_e32 v241, 2, v241
	global_load_dwordx4 v[224:227], v[242:243], off nt
	global_load_dwordx4 v[228:231], v[242:243], off offset:1024 nt
	global_load_dwordx4 v[232:235], v[242:243], off offset:2048 nt
	global_load_dwordx4 v[236:239], v[242:243], off offset:3072 nt
	s_waitcnt vmcnt(0)
	v_add_f32_e32 v208, v208, v209
	v_add_f32_e32 v210, v210, v211
	v_add_f32_e32 v212, v212, v213
	v_add_f32_e32 v214, v214, v215
	v_add_f32_e32 v216, v216, v217
	v_add_f32_e32 v218, v218, v219
	v_add_f32_e32 v220, v220, v221
	v_add_f32_e32 v222, v222, v223
	v_add_f32_e32 v224, v224, v225
	v_add_f32_e32 v226, v226, v227
	v_add_f32_e32 v228, v228, v229
	v_add_f32_e32 v230, v230, v231
	v_add_f32_e32 v232, v232, v233
	v_add_f32_e32 v234, v234, v235
	v_add_f32_e32 v236, v236, v237
	v_add_f32_e32 v238, v238, v239
	v_add_f32_e32 v208, v208, v210
	v_add_f32_e32 v212, v212, v214
	v_add_f32_e32 v216, v216, v218
	v_add_f32_e32 v220, v220, v222
	v_add_f32_e32 v224, v224, v226
	v_add_f32_e32 v228, v228, v230
	v_add_f32_e32 v232, v232, v234
	v_add_f32_e32 v236, v236, v238
	ds_bpermute_b32 v209, v240, v208
	ds_bpermute_b32 v213, v240, v212
	ds_bpermute_b32 v217, v240, v216
	ds_bpermute_b32 v221, v240, v220
	ds_bpermute_b32 v225, v240, v224
	ds_bpermute_b32 v229, v240, v228
	ds_bpermute_b32 v233, v240, v232
	ds_bpermute_b32 v237, v240, v236
	s_waitcnt lgkmcnt(0)
	v_add_f32_e32 v208, v208, v209
	v_add_f32_e32 v212, v212, v213
	v_add_f32_e32 v216, v216, v217
	v_add_f32_e32 v220, v220, v221
	v_add_f32_e32 v224, v224, v225
	v_add_f32_e32 v228, v228, v229
	v_add_f32_e32 v232, v232, v233
	v_add_f32_e32 v236, v236, v237
	ds_bpermute_b32 v209, v241, v208
	ds_bpermute_b32 v213, v241, v212
	ds_bpermute_b32 v217, v241, v216
	ds_bpermute_b32 v221, v241, v220
	ds_bpermute_b32 v225, v241, v224
	ds_bpermute_b32 v229, v241, v228
	ds_bpermute_b32 v233, v241, v232
	ds_bpermute_b32 v237, v241, v236
	s_waitcnt lgkmcnt(0)
	v_add_f32_e32 v208, v208, v209
	v_add_f32_e32 v212, v212, v213
	v_add_f32_e32 v216, v216, v217
	v_add_f32_e32 v220, v220, v221
	v_add_f32_e32 v224, v224, v225
	v_add_f32_e32 v228, v228, v229
	v_add_f32_e32 v232, v232, v233
	v_add_f32_e32 v236, v236, v237
	v_fmamk_f32 v208, v208, 0x3a800000, v170
	v_fmamk_f32 v212, v212, 0x3a800000, v170
	v_fmamk_f32 v216, v216, 0x3a800000, v170
	v_fmamk_f32 v220, v220, 0x3a800000, v170
	v_fmamk_f32 v224, v224, 0x3a800000, v170
	v_fmamk_f32 v228, v228, 0x3a800000, v170
	v_fmamk_f32 v232, v232, 0x3a800000, v170
	v_fmamk_f32 v236, v236, 0x3a800000, v170
	v_div_scale_f32 v209, vcc, v208, v208, 1.0
	v_rcp_f32_e32 v210, v209
	v_div_scale_f32 v211, vcc, 1.0, v208, 1.0
	v_fma_f32 v240, -v209, v210, 1.0
	v_fmac_f32_e32 v210, v240, v210
	v_mul_f32_e32 v241, v211, v210
	v_fma_f32 v240, -v209, v241, v211
	v_fmac_f32_e32 v241, v240, v210
	v_fma_f32 v240, -v209, v241, v211
	v_div_fmas_f32 v240, v240, v210, v241
	v_div_fixup_f32 v245, v240, v208, 1.0
	v_div_scale_f32 v213, vcc, v212, v212, 1.0
	v_rcp_f32_e32 v214, v213
	v_div_scale_f32 v215, vcc, 1.0, v212, 1.0
	v_fma_f32 v240, -v213, v214, 1.0
	v_fmac_f32_e32 v214, v240, v214
	v_mul_f32_e32 v241, v215, v214
	v_fma_f32 v240, -v213, v241, v215
	v_fmac_f32_e32 v241, v240, v214
	v_fma_f32 v240, -v213, v241, v215
	v_div_fmas_f32 v240, v240, v214, v241
	v_div_fixup_f32 v246, v240, v212, 1.0
	v_div_scale_f32 v217, vcc, v216, v216, 1.0
	v_rcp_f32_e32 v218, v217
	v_div_scale_f32 v219, vcc, 1.0, v216, 1.0
	v_fma_f32 v240, -v217, v218, 1.0
	v_fmac_f32_e32 v218, v240, v218
	v_mul_f32_e32 v241, v219, v218
	v_fma_f32 v240, -v217, v241, v219
	v_fmac_f32_e32 v241, v240, v218
	v_fma_f32 v240, -v217, v241, v219
	v_div_fmas_f32 v240, v240, v218, v241
	v_div_fixup_f32 v247, v240, v216, 1.0
	v_div_scale_f32 v221, vcc, v220, v220, 1.0
	v_rcp_f32_e32 v222, v221
	v_div_scale_f32 v223, vcc, 1.0, v220, 1.0
	v_fma_f32 v240, -v221, v222, 1.0
	v_fmac_f32_e32 v222, v240, v222
	v_mul_f32_e32 v241, v223, v222
	v_fma_f32 v240, -v221, v241, v223
	v_fmac_f32_e32 v241, v240, v222
	v_fma_f32 v240, -v221, v241, v223
	v_div_fmas_f32 v240, v240, v222, v241
	v_div_fixup_f32 v248, v240, v220, 1.0
	v_div_scale_f32 v225, vcc, v224, v224, 1.0
	v_rcp_f32_e32 v226, v225
	v_div_scale_f32 v227, vcc, 1.0, v224, 1.0
	v_fma_f32 v240, -v225, v226, 1.0
	v_fmac_f32_e32 v226, v240, v226
	v_mul_f32_e32 v241, v227, v226
	v_fma_f32 v240, -v225, v241, v227
	v_fmac_f32_e32 v241, v240, v226
	v_fma_f32 v240, -v225, v241, v227
	v_div_fmas_f32 v240, v240, v226, v241
	v_div_fixup_f32 v249, v240, v224, 1.0
	v_div_scale_f32 v229, vcc, v228, v228, 1.0
	v_rcp_f32_e32 v230, v229
	v_div_scale_f32 v231, vcc, 1.0, v228, 1.0
	v_fma_f32 v240, -v229, v230, 1.0
	v_fmac_f32_e32 v230, v240, v230
	v_mul_f32_e32 v241, v231, v230
	v_fma_f32 v240, -v229, v241, v231
	v_fmac_f32_e32 v241, v240, v230
	v_fma_f32 v240, -v229, v241, v231
	v_div_fmas_f32 v240, v240, v230, v241
	v_div_fixup_f32 v250, v240, v228, 1.0
	v_div_scale_f32 v233, vcc, v232, v232, 1.0
	v_rcp_f32_e32 v234, v233
	v_div_scale_f32 v235, vcc, 1.0, v232, 1.0
	v_fma_f32 v240, -v233, v234, 1.0
	v_fmac_f32_e32 v234, v240, v234
	v_mul_f32_e32 v241, v235, v234
	v_fma_f32 v240, -v233, v241, v235
	v_fmac_f32_e32 v241, v240, v234
	v_fma_f32 v240, -v233, v241, v235
	v_div_fmas_f32 v240, v240, v234, v241
	v_div_fixup_f32 v251, v240, v232, 1.0
	v_div_scale_f32 v237, vcc, v236, v236, 1.0
	v_rcp_f32_e32 v238, v237
	v_div_scale_f32 v239, vcc, 1.0, v236, 1.0
	v_fma_f32 v240, -v237, v238, 1.0
	v_fmac_f32_e32 v238, v240, v238
	v_mul_f32_e32 v241, v239, v238
	v_fma_f32 v240, -v237, v241, v239
	v_fmac_f32_e32 v241, v240, v238
	v_fma_f32 v240, -v237, v241, v239
	v_div_fmas_f32 v240, v240, v238, v241
	v_div_fixup_f32 v252, v240, v236, 1.0
.Lp4_r2_cached0:
	s_barrier
	s_branch .LBB0_531

; __global__ void __launch_bounds__(NWAVES * 64, 2) hymba_fwd(Args args) {
	.amdhsa_kernel _Z9hymba_fwd4Args
		.amdhsa_group_segment_fixed_size 0
		.amdhsa_private_segment_fixed_size 0
		.amdhsa_kernarg_size 384
		.amdhsa_user_sgpr_count 2
		.amdhsa_user_sgpr_dispatch_ptr 0
		.amdhsa_user_sgpr_queue_ptr 0
		.amdhsa_user_sgpr_kernarg_segment_ptr 1
		.amdhsa_user_sgpr_dispatch_id 0
		.amdhsa_user_sgpr_kernarg_preload_length 0
		.amdhsa_user_sgpr_kernarg_preload_offset 0
		.amdhsa_user_sgpr_private_segment_size 0
		.amdhsa_uses_dynamic_stack 0
		.amdhsa_enable_private_segment 0
		.amdhsa_system_sgpr_workgroup_id_x 1
		.amdhsa_system_sgpr_workgroup_id_y 0
		.amdhsa_system_sgpr_workgroup_id_z 0
		.amdhsa_system_sgpr_workgroup_info 0
		.amdhsa_system_vgpr_workitem_id 2
		.amdhsa_next_free_vgpr 254
		.amdhsa_next_free_sgpr 102
		.amdhsa_accum_offset 256
		.amdhsa_reserve_vcc 1
		.amdhsa_float_round_mode_32 0
		.amdhsa_float_round_mode_16_64 0
		.amdhsa_float_denorm_mode_32 3
		.amdhsa_float_denorm_mode_16_64 3
		.amdhsa_dx10_clamp 1
		.amdhsa_ieee_mode 1
		.amdhsa_fp16_overflow 0
		.amdhsa_tg_split 0
		.amdhsa_exception_fp_ieee_invalid_op 0
		.amdhsa_exception_fp_denorm_src 0
		.amdhsa_exception_fp_ieee_div_zero 0
		.amdhsa_exception_fp_ieee_overflow 0
		.amdhsa_exception_fp_ieee_underflow 0
		.amdhsa_exception_fp_ieee_inexact 0
		.amdhsa_exception_int_div_zero 0
	.end_amdhsa_kernel

; __global__ void __launch_bounds__(NWAVES * 64, 2) hymba_fwd(Args args) {
amdhsa.kernels:
  - .agpr_count:     0
    .args:
      - .offset:         0
        .size:           128
        .value_kind:     by_value
      - .offset:         128
        .size:           4
        .value_kind:     hidden_block_count_x
      - .offset:         132
        .size:           4
        .value_kind:     hidden_block_count_y
      - .offset:         136
        .size:           4
        .value_kind:     hidden_block_count_z
      - .offset:         140
        .size:           2
        .value_kind:     hidden_group_size_x
      - .offset:         142
        .size:           2
        .value_kind:     hidden_group_size_y
      - .offset:         144
        .size:           2
        .value_kind:     hidden_group_size_z
      - .offset:         146
        .size:           2
        .value_kind:     hidden_remainder_x
      - .offset:         148
        .size:           2
        .value_kind:     hidden_remainder_y
      - .offset:         150
        .size:           2
        .value_kind:     hidden_remainder_z
      - .offset:         168
        .size:           8
        .value_kind:     hidden_global_offset_x
      - .offset:         176
        .size:           8
        .value_kind:     hidden_global_offset_y
      - .offset:         184
        .size:           8
        .value_kind:     hidden_global_offset_z
      - .offset:         192
        .size:           2
        .value_kind:     hidden_grid_dims
      - .offset:         216
        .size:           8
        .value_kind:     hidden_multigrid_sync_arg
      - .offset:         248
        .size:           4
        .value_kind:     hidden_dynamic_lds_size
    .group_segment_fixed_size: 0
    .kernarg_segment_align: 8
    .kernarg_segment_size: 384
    .language:       OpenCL C
    .language_version:
      - 2
      - 0
    .max_flat_workgroup_size: 512
    .name:           _Z9hymba_fwd4Args
    .private_segment_fixed_size: 0
    .sgpr_count:     108
    .sgpr_spill_count: 36
    .symbol:         _Z9hymba_fwd4Args.kd
    .uniform_work_group_size: 1
    .uses_dynamic_stack: false
    .vgpr_count:     254
    .vgpr_spill_count: 0
    .wavefront_size: 64
